# split-K (2-way, flag handoff) of the half-empty last tile round of the L0 MLP-up GEMM phase
# speedup vs baseline: 1.0034x; 1.0034x over previous
.LBB0_816:
	s_cmp_lt_i32 s78, 8
	s_cselect_b64 s[0:1], -1, 0
	s_cmp_gt_i32 s79, 7
	s_cselect_b64 s[2:3], -1, 0
	s_and_b64 s[0:1], s[0:1], s[2:3]
	s_andn2_b64 vcc, exec, s[0:1]
	s_cbranch_vccnz .LBB0_888
	s_waitcnt vmcnt(0)
	v_mbcnt_hi_u32_b32 v9, -1, v212
	s_cmpk_gt_i32 s96, 0x47f
	v_and_b32_e32 v146, 63, v9
	s_cbranch_scc1 .LBB0_833
	s_mov_b32 s98, 28
	s_mov_b32 s99, 29
	s_mov_b32 s100, -1
	s_mov_b32 s101, -1
	s_add_u32 s30, s76, 0x11189000
	s_addc_u32 s31, s77, 0
	s_add_u32 s33, s76, 0x4989000
	s_addc_u32 s34, s77, 0
	s_lshl_b32 s35, s93, 10
	v_lshl_or_b32 v0, v146, 4, s35
	v_add_u32_e32 v1, 0x2000, v0
	v_ashrrev_i32_e32 v2, 31, v1
	v_lshrrev_b32_e32 v2, 22, v2
	v_add_u32_e32 v2, v1, v2
	v_ashrrev_i32_e32 v8, 10, v2
	v_mul_i32_i24_e32 v2, 0x400, v8
	v_sub_u32_e32 v1, v1, v2
	v_lshrrev_b32_e32 v2, 4, v1
	v_bitop3_b32 v1, v2, v1, 32 bitop3:0x6c
	v_ashrrev_i32_e32 v2, 31, v1
	v_lshrrev_b32_e32 v2, 26, v2
	v_add_u32_e32 v2, v1, v2
	v_ashrrev_i32_e32 v10, 6, v2
	v_lshlrev_b32_e32 v3, 3, v8
	v_and_b32_e32 v2, 0xffc0, v2
	v_and_b32_e32 v3, -16, v3
	v_sub_u32_e32 v1, v1, v2
	v_add_u32_e32 v3, v10, v3
	v_lshrrev_b16_e32 v2, 7, v1
	v_and_b32_e32 v4, 3, v10
	s_mov_b32 s0, 0xfffe0
	v_lshrrev_b32_e32 v5, 2, v3
	v_lshlrev_b32_e32 v6, 1, v3
	v_and_b32_e32 v2, 1, v2
	v_and_or_b32 v4, v3, s0, v4
	v_and_b32_e32 v5, 4, v5
	v_and_b32_e32 v6, 24, v6
	v_add_u16_e32 v1, v1, v2
	v_mov_b32_e32 v2, 1
	v_or3_b32 v4, v4, v5, v6
	v_lshlrev_b32_e32 v5, 5, v8
	v_ashrrev_i16_sdwa v1, v2, sext(v1) dst_sel:DWORD dst_unused:UNUSED_PAD src0_sel:DWORD src1_sel:BYTE_0
	v_and_b32_e32 v5, 32, v5
	v_bfe_i32 v11, v1, 0, 16
	v_add_lshl_u32 v1, v5, v11, 1
	v_lshl_add_u32 v128, v4, 12, v1
	v_lshl_add_u32 v130, v3, 12, v1
	v_ashrrev_i32_e32 v1, 31, v0
	v_lshrrev_b32_e32 v1, 22, v1
	v_add_u32_e32 v1, v0, v1
	v_ashrrev_i32_e32 v12, 10, v1
	v_mul_i32_i24_e32 v1, 0x400, v12
	v_sub_u32_e32 v0, v0, v1
	v_lshrrev_b32_e32 v1, 4, v0
	v_bitop3_b32 v0, v1, v0, 32 bitop3:0x6c
	v_ashrrev_i32_e32 v1, 31, v0
	v_lshrrev_b32_e32 v1, 26, v1
	v_add_u32_e32 v1, v0, v1
	v_lshlrev_b32_e32 v3, 3, v12
	v_ashrrev_i32_e32 v13, 6, v1
	v_and_b32_e32 v3, -16, v3
	v_add_u32_e32 v3, v13, v3
	v_and_b32_e32 v4, 3, v13
	s_ashr_i32 s36, s96, 31
	v_and_or_b32 v4, v3, s0, v4
	s_lshr_b32 s0, s36, 29
	s_add_i32 s0, s96, s0
	s_ashr_i32 s2, s0, 3
	s_and_b32 s0, s0, -8
	s_lshr_b32 s1, s92, 8
	s_sub_i32 s0, s96, s0
	s_cmp_lt_i32 s0, 0
	s_movk_i32 s37, 0x91
	s_cselect_b32 s3, s37, 0x90
	s_mul_i32 s0, s0, s3
	s_add_i32 s0, s0, s2
	s_ashr_i32 s2, s0, 31
	s_lshr_b32 s2, s2, 25
	s_add_i32 s2, s0, s2
	s_ashr_i32 s3, s2, 7
	s_and_b32 s2, s2, 0xff80
	s_sub_i32 s0, s0, s2
	s_bfe_i32 s2, s0, 0x80000
	s_bfe_u32 s2, s2, 0x2000d
	s_add_i32 s2, s0, s2
	s_and_b32 s4, s2, 0xfc
	s_sub_i32 s0, s0, s4
	s_lshl_b32 s3, s3, 2
	s_sext_i32_i8 s0, s0
	s_add_i32 s20, s3, s0
	s_bfe_i32 s0, s2, 0x80000
	s_sext_i32_i16 s0, s0
	s_ashr_i32 s21, s20, 31
	s_lshr_b32 s0, s0, 2
	s_lshl_b64 s[2:3], s[20:21], 20
	v_lshrrev_b32_e32 v5, 2, v3
	v_lshlrev_b32_e32 v6, 1, v3
	v_and_b32_e32 v1, 0xc0, v1
	s_add_u32 s22, s30, s2
	v_and_b32_e32 v5, 4, v5
	v_and_b32_e32 v6, 24, v6
	v_sub_u32_e32 v0, v0, v1
	s_addc_u32 s23, s31, s3
	s_bfe_i64 s[2:3], s[0:1], 0x100000
	v_or3_b32 v4, v4, v5, v6
	v_lshlrev_b32_e32 v5, 5, v12
	v_ashrrev_i16_sdwa v0, v2, sext(v0) dst_sel:DWORD dst_unused:UNUSED_PAD src0_sel:DWORD src1_sel:BYTE_0
	s_lshl_b64 s[2:3], s[2:3], 20
	v_and_b32_e32 v5, 32, v5
	v_bfe_i32 v14, v0, 0, 16
	s_add_u32 s24, s33, s2
	v_add_lshl_u32 v0, v5, v14, 1
	s_addc_u32 s25, s34, s3
	s_add_i32 s38, s35, 0
	v_lshl_add_u32 v132, v4, 12, v0
	s_add_i32 m0, s38, 0x10000
	v_lshl_add_u32 v134, v3, 12, v0
	global_load_lds_dwordx4 v132, s[24:25]
	s_add_i32 m0, s38, 0x12000
	s_add_u32 s2, s24, 0x80000
	global_load_lds_dwordx4 v128, s[24:25]
	s_addc_u32 s3, s25, 0
	s_add_i32 m0, s38, 0x14000
	s_add_i32 s39, s38, 0x2000
	global_load_lds_dwordx4 v132, s[2:3]
	s_add_i32 m0, s38, 0x16000
	v_mov_b32_e32 v133, 0
	global_load_lds_dwordx4 v128, s[2:3]
	s_mov_b32 m0, s38
	s_add_u32 s2, s22, 0x80000
	global_load_lds_dwordx4 v134, s[22:23]
	s_mov_b32 m0, s39
	s_addc_u32 s3, s23, 0
	s_add_i32 s40, s38, 0x4000
	global_load_lds_dwordx4 v130, s[22:23]
	s_mov_b32 m0, s40
	s_add_i32 s41, s38, 0x6000
	global_load_lds_dwordx4 v134, s[2:3]
	s_mov_b32 m0, s41
	v_mov_b32_e32 v129, v133
	global_load_lds_dwordx4 v130, s[2:3]
	v_mov_b32_e32 v135, v133
	v_mov_b32_e32 v131, v133
	s_cmp_eq_u32 s1, 1
	v_lshl_add_u64 v[6:7], s[24:25], 0, v[132:133]
	v_lshl_add_u64 v[4:5], s[24:25], 0, v[128:129]
	v_lshl_add_u64 v[0:1], s[22:23], 0, v[134:135]
	s_cselect_b64 s[2:3], -1, 0
	s_cmp_lg_u32 s1, 1
	v_lshl_add_u64 v[2:3], s[22:23], 0, v[130:131]
	s_cbranch_scc1 .LBB0_820
	s_barrier
.LBB0_820:
	s_add_u32 s42, s76, 0x13589000
	s_addc_u32 s43, s77, 0
	s_bfe_u32 s4, s92, 0x20006
	s_lshl_b32 s12, s4, 5
	s_lshl_b32 s10, s4, 12
	s_mov_b64 s[4:5], 0x80
	s_add_i32 m0, s38, 0x18000
	v_lshl_add_u64 v[6:7], v[6:7], 0, s[4:5]
	s_lshl_b32 s44, s1, 6
	s_lshl_b32 s1, s1, 13
	s_waitcnt vmcnt(2)
	s_barrier
	global_load_lds_dwordx4 v[6:7], off
	v_lshl_add_u64 v[4:5], v[4:5], 0, s[4:5]
	s_add_i32 m0, s38, 0x1a000
	s_add_i32 s45, s38, 0x8000
	s_add_i32 s46, s38, 0xa000
	global_load_lds_dwordx4 v[4:5], off
	v_lshl_add_u64 v[0:1], v[0:1], 0, s[4:5]
	s_mov_b32 m0, s45
	s_add_u32 s6, s24, 0x80080
	global_load_lds_dwordx4 v[0:1], off
	v_lshl_add_u64 v[0:1], v[2:3], 0, s[4:5]
	s_mov_b32 m0, s46
	s_addc_u32 s7, s25, 0
	global_load_lds_dwordx4 v[0:1], off
	s_add_i32 m0, s38, 0x1c000
	v_lshl_add_u64 v[0:1], s[6:7], 0, v[132:133]
	global_load_lds_dwordx4 v[0:1], off
	v_lshl_add_u64 v[0:1], s[6:7], 0, v[128:129]
	s_add_i32 m0, s38, 0x1e000
	v_and_b32_e32 v147, 15, v9
	global_load_lds_dwordx4 v[0:1], off
	v_and_b32_e32 v0, 48, v9
	v_lshlrev_b32_e32 v1, 2, v9
	v_lshl_or_b32 v0, v147, 6, v0
	v_and_b32_e32 v1, 32, v1
	v_bitop3_b32 v2, v0, s1, v1 bitop3:0xde
	v_bitop3_b32 v149, v0, s10, v1 bitop3:0xde
	v_lshlrev_b32_e32 v0, 15, v12
	v_and_b32_e32 v0, 0xffff0000, v0
	v_lshl_add_u32 v0, v13, 12, v0
	v_and_b32_e32 v1, 1, v12
	v_lshl_or_b32 v0, v1, 6, v0
	v_lshl_add_u32 v136, v14, 1, v0
	v_lshlrev_b32_e32 v0, 15, v8
	v_and_b32_e32 v0, 0xffff0000, v0
	s_waitcnt vmcnt(6)
	s_cmpk_lt_u32 s92, 0x100
	v_lshl_add_u32 v0, v10, 12, v0
	v_and_b32_e32 v1, 1, v8
	s_mov_b32 s7, 0
	s_cselect_b64 s[10:11], -1, 0
	v_lshl_or_b32 v0, v1, 6, v0
	s_add_i32 s48, 0, 0x10000
	s_add_i32 s49, 0, 0x14000
	s_sext_i32_i8 s21, s0
	v_lshrrev_b32_e32 v148, 4, v146
	s_ashr_i32 s47, s87, 31
	v_mov_b32_e32 v137, v133
	v_lshl_add_u32 v138, v11, 1, v0
	v_mov_b32_e32 v139, v133
	v_mov_b64_e32 v[140:141], 0x500
	v_mov_b64_e32 v[142:143], 0x4ff
	v_add_u32_e32 v150, s48, v149
	v_add_u32_e32 v151, s49, v149
	v_add_u32_e32 v152, 0, v2
	s_lshl_b32 s6, s12, 1
	s_mov_b32 s50, s7
	s_barrier
	s_branch .LBB0_823

.LBB0_822:
	s_andn2_b64 vcc, exec, s[0:1]
	s_mov_b32 s21, s12
	s_mov_b32 s100, s101
	s_cmp_lt_i32 s100, 0
	s_cselect_b32 s98, 28, 12
	s_cselect_b32 s99, 29, 13
	s_mov_b32 s20, s14
	s_mov_b64 s[24:25], s[18:19]
	s_mov_b64 s[22:23], s[16:17]
	s_cbranch_vccz .LBB0_832
.LBB0_823:
	s_add_i32 s50, s50, 1
	s_mul_i32 s0, s50, s47
	s_mul_hi_u32 s1, s50, s87
	s_add_i32 s1, s1, s0
	s_mul_i32 s0, s50, s87
	s_add_u32 s16, s0, s96
	s_addc_u32 s17, s1, s36
	v_cmp_gt_i64_e32 vcc, s[16:17], v[142:143]
	v_cmp_lt_i64_e64 s[0:1], s[16:17], v[140:141]
	s_cbranch_vccnz .LBB0_825
	s_mov_b32 s101, -1
	s_cmp_lt_u32 s16, 0x400
	s_cbranch_scc1 .Lsk7_full
	s_sub_u32 s101, s16, 0x400
	s_and_b32 s16, s101, 0x7f
	s_add_u32 s16, s16, 0x400
.Lsk7_full:
	s_ashr_i32 s12, s16, 31
	s_lshr_b32 s12, s12, 29
	s_add_i32 s12, s16, s12
	s_ashr_i32 s13, s12, 3
	s_and_b32 s12, s12, -8
	s_sub_i32 s12, s16, s12
	s_cmp_lt_i32 s12, 0
	s_cselect_b32 s14, s37, 0x90
	s_mul_i32 s12, s12, s14
	s_add_i32 s12, s12, s13
	s_ashr_i32 s13, s12, 31
	s_lshr_b32 s13, s13, 25
	s_add_i32 s13, s12, s13
	s_ashr_i32 s14, s13, 7
	s_lshl_b32 s14, s14, 2
	s_sub_i32 s15, 36, s14
	s_min_i32 s15, s15, 4
	s_abs_i32 s16, s15
	v_cvt_f32_u32_e32 v0, s16
	s_sub_i32 s18, 0, s16
	s_and_b32 s13, s13, 0xffffff80
	s_sub_i32 s13, s12, s13
	v_rcp_iflag_f32_e32 v0, v0
	s_abs_i32 s12, s13
	s_xor_b32 s17, s13, s15
	s_ashr_i32 s17, s17, 31
	v_mul_f32_e32 v0, 0x4f7ffffe, v0
	v_cvt_u32_f32_e32 v0, v0
	s_nop 0
	v_readfirstlane_b32 s19, v0
	s_mul_i32 s18, s18, s19
	s_mul_hi_u32 s18, s19, s18
	s_add_i32 s19, s19, s18
	s_mul_hi_u32 s18, s12, s19
	s_mul_i32 s19, s18, s16
	s_sub_i32 s12, s12, s19
	s_add_i32 s26, s18, 1
	s_sub_i32 s19, s12, s16
	s_cmp_ge_u32 s12, s16
	s_cselect_b32 s18, s26, s18
	s_cselect_b32 s12, s19, s12
	s_add_i32 s19, s18, 1
	s_cmp_ge_u32 s12, s16
	s_cselect_b32 s12, s19, s18
	s_xor_b32 s12, s12, s17
	s_sub_i32 s12, s12, s17
	s_mul_i32 s15, s12, s15
	s_sub_i32 s13, s13, s15
	s_add_i32 s14, s14, s13
.LBB0_825:
	s_ashr_i32 s15, s14, 31
	s_lshl_b64 s[16:17], s[14:15], 20
	s_add_u32 s16, s30, s16
	s_addc_u32 s17, s31, s17
	s_max_i32 s26, s101, 0
	s_lshr_b32 s26, s26, 7
	s_lshl_b32 s26, s26, 11
	s_add_u32 s16, s16, s26
	s_addc_u32 s17, s17, 0
	s_and_b64 s[18:19], s[0:1], exec
	s_cselect_b32 s15, s17, s23
	s_cselect_b32 s51, s16, s22
	s_ashr_i32 s13, s12, 31
	s_lshl_b64 s[18:19], s[12:13], 20
	s_add_u32 s18, s33, s18
	s_addc_u32 s19, s34, s19
	s_add_u32 s18, s18, s26
	s_addc_u32 s19, s19, 0
	s_and_b64 s[26:27], s[0:1], exec
	s_cselect_b32 s13, s19, s25
	s_cselect_b32 s52, s18, s24
	s_add_u32 s22, s22, 0x80080
	s_addc_u32 s23, s23, 0
	s_add_u32 s53, s24, 0x100
	v_mov_b32_e32 v0, 0
	s_addc_u32 s54, s25, 0
	s_mov_b32 s55, -2
	v_mov_b32_e32 v1, v0
	v_mov_b32_e32 v2, v0
	v_mov_b32_e32 v3, v0
	v_mov_b32_e32 v4, v0
	v_mov_b32_e32 v5, v0
	v_mov_b32_e32 v6, v0
	v_mov_b32_e32 v7, v0
	v_mov_b32_e32 v16, v0
	v_mov_b32_e32 v17, v0
	v_mov_b32_e32 v18, v0
	v_mov_b32_e32 v19, v0
	v_mov_b32_e32 v20, v0
	v_mov_b32_e32 v21, v0
	v_mov_b32_e32 v22, v0
	v_mov_b32_e32 v23, v0
	v_mov_b32_e32 v32, v0
	v_mov_b32_e32 v33, v0
	v_mov_b32_e32 v34, v0
	v_mov_b32_e32 v35, v0
	v_mov_b32_e32 v36, v0
	v_mov_b32_e32 v37, v0
	v_mov_b32_e32 v38, v0
	v_mov_b32_e32 v39, v0
	v_mov_b32_e32 v48, v0
	v_mov_b32_e32 v49, v0
	v_mov_b32_e32 v50, v0
	v_mov_b32_e32 v51, v0
	v_mov_b32_e32 v52, v0
	v_mov_b32_e32 v53, v0
	v_mov_b32_e32 v54, v0
	v_mov_b32_e32 v55, v0
	v_mov_b32_e32 v8, v0
	v_mov_b32_e32 v9, v0
	v_mov_b32_e32 v10, v0
	v_mov_b32_e32 v11, v0
	v_mov_b32_e32 v12, v0
	v_mov_b32_e32 v13, v0
	v_mov_b32_e32 v14, v0
	v_mov_b32_e32 v15, v0
	v_mov_b32_e32 v24, v0
	v_mov_b32_e32 v25, v0
	v_mov_b32_e32 v26, v0
	v_mov_b32_e32 v27, v0
	v_mov_b32_e32 v28, v0
	v_mov_b32_e32 v29, v0
	v_mov_b32_e32 v30, v0
	v_mov_b32_e32 v31, v0
	v_mov_b32_e32 v40, v0
	v_mov_b32_e32 v41, v0
	v_mov_b32_e32 v42, v0
	v_mov_b32_e32 v43, v0
	v_mov_b32_e32 v44, v0
	v_mov_b32_e32 v45, v0
	v_mov_b32_e32 v46, v0
	v_mov_b32_e32 v47, v0
	v_mov_b32_e32 v56, v0
	v_mov_b32_e32 v57, v0
	v_mov_b32_e32 v58, v0
	v_mov_b32_e32 v59, v0
	v_mov_b32_e32 v60, v0
	v_mov_b32_e32 v61, v0
	v_mov_b32_e32 v62, v0
	v_mov_b32_e32 v63, v0
	v_mov_b32_e32 v64, v0
	v_mov_b32_e32 v65, v0
	v_mov_b32_e32 v66, v0
	v_mov_b32_e32 v67, v0
	v_mov_b32_e32 v68, v0
	v_mov_b32_e32 v69, v0
	v_mov_b32_e32 v70, v0
	v_mov_b32_e32 v71, v0
	v_mov_b32_e32 v80, v0
	v_mov_b32_e32 v81, v0
	v_mov_b32_e32 v82, v0
	v_mov_b32_e32 v83, v0
	v_mov_b32_e32 v84, v0
	v_mov_b32_e32 v85, v0
	v_mov_b32_e32 v86, v0
	v_mov_b32_e32 v87, v0
	v_mov_b32_e32 v96, v0
	v_mov_b32_e32 v97, v0
	v_mov_b32_e32 v98, v0
	v_mov_b32_e32 v99, v0
	v_mov_b32_e32 v100, v0
	v_mov_b32_e32 v101, v0
	v_mov_b32_e32 v102, v0
	v_mov_b32_e32 v103, v0
	v_mov_b32_e32 v112, v0
	v_mov_b32_e32 v113, v0
	v_mov_b32_e32 v114, v0
	v_mov_b32_e32 v115, v0
	v_mov_b32_e32 v116, v0
	v_mov_b32_e32 v117, v0
	v_mov_b32_e32 v118, v0
	v_mov_b32_e32 v119, v0
	v_mov_b32_e32 v72, v0
	v_mov_b32_e32 v73, v0
	v_mov_b32_e32 v74, v0
	v_mov_b32_e32 v75, v0
	v_mov_b32_e32 v76, v0
	v_mov_b32_e32 v77, v0
	v_mov_b32_e32 v78, v0
	v_mov_b32_e32 v79, v0
	v_mov_b32_e32 v88, v0
	v_mov_b32_e32 v89, v0
	v_mov_b32_e32 v90, v0
	v_mov_b32_e32 v91, v0
	v_mov_b32_e32 v92, v0
	v_mov_b32_e32 v93, v0
	v_mov_b32_e32 v94, v0
	v_mov_b32_e32 v95, v0
	v_mov_b32_e32 v104, v0
	v_mov_b32_e32 v105, v0
	v_mov_b32_e32 v106, v0
	v_mov_b32_e32 v107, v0
	v_mov_b32_e32 v108, v0
	v_mov_b32_e32 v109, v0
	v_mov_b32_e32 v110, v0
	v_mov_b32_e32 v111, v0
	v_mov_b32_e32 v120, v0
	v_mov_b32_e32 v121, v0
	v_mov_b32_e32 v122, v0
	v_mov_b32_e32 v123, v0
	v_mov_b32_e32 v124, v0
	v_mov_b32_e32 v125, v0
	v_mov_b32_e32 v126, v0
	v_mov_b32_e32 v127, v0
.LBB0_826:
	ds_read_b128 v[154:157], v150
	ds_read_b128 v[158:161], v150 offset:1024
	ds_read_b128 v[162:165], v150 offset:2048
	ds_read_b128 v[166:169], v150 offset:3072
	ds_read_b128 v[170:173], v151
	ds_read_b128 v[174:177], v151 offset:1024
	ds_read_b128 v[178:181], v151 offset:2048
	ds_read_b128 v[182:185], v151 offset:3072
	s_add_u32 s24, s22, 0xfff80080
	s_addc_u32 s25, s23, -1
	s_cmp_eq_u32 s55, s98
	s_cselect_b32 s27, s15, s25
	s_cselect_b32 s26, s51, s24
	s_cselect_b32 s25, s13, s54
	s_cselect_b32 s24, s52, s53
	v_lshl_add_u64 v[144:145], s[22:23], 0, v[136:137]
	s_add_i32 m0, s38, 0xc000
	ds_read_b128 v[186:189], v152
	ds_read_b128 v[190:193], v152 offset:1024
	ds_read_b128 v[194:197], v152 offset:2048
	ds_read_b128 v[198:201], v152 offset:3072
	ds_read_b128 v[202:205], v152 offset:4096
	ds_read_b128 v[206:209], v152 offset:5120
	ds_read_b128 v[214:217], v152 offset:6144
	ds_read_b128 v[218:221], v152 offset:7168
	global_load_lds_dwordx4 v[144:145], off
	v_lshl_add_u64 v[144:145], s[22:23], 0, v[138:139]
	s_add_i32 m0, s38, 0xe000
	s_nop 0
	global_load_lds_dwordx4 v[144:145], off
	s_waitcnt vmcnt(8)
	s_waitcnt lgkmcnt(0)
	s_barrier
	s_setprio 1
	s_waitcnt lgkmcnt(0)
	v_mfma_f32_16x16x32_bf16 v[124:127], v[154:157], v[186:189], v[124:127]
	v_mfma_f32_16x16x32_bf16 v[120:123], v[162:165], v[186:189], v[120:123]
	v_mfma_f32_16x16x32_bf16 v[108:111], v[154:157], v[194:197], v[108:111]
	v_mfma_f32_16x16x32_bf16 v[104:107], v[162:165], v[194:197], v[104:107]
	v_mfma_f32_16x16x32_bf16 v[92:95], v[154:157], v[202:205], v[92:95]
	v_mfma_f32_16x16x32_bf16 v[88:91], v[162:165], v[202:205], v[88:91]
	v_mfma_f32_16x16x32_bf16 v[76:79], v[154:157], v[214:217], v[76:79]
	v_mfma_f32_16x16x32_bf16 v[72:75], v[162:165], v[214:217], v[72:75]
	v_mfma_f32_16x16x32_bf16 v[124:127], v[158:161], v[190:193], v[124:127]
	v_mfma_f32_16x16x32_bf16 v[120:123], v[166:169], v[190:193], v[120:123]
	v_mfma_f32_16x16x32_bf16 v[108:111], v[158:161], v[198:201], v[108:111]
	v_mfma_f32_16x16x32_bf16 v[104:107], v[166:169], v[198:201], v[104:107]
	v_mfma_f32_16x16x32_bf16 v[92:95], v[158:161], v[206:209], v[92:95]
	v_mfma_f32_16x16x32_bf16 v[88:91], v[166:169], v[206:209], v[88:91]
	v_mfma_f32_16x16x32_bf16 v[76:79], v[158:161], v[218:221], v[76:79]
	v_mfma_f32_16x16x32_bf16 v[72:75], v[166:169], v[218:221], v[72:75]
	s_setprio 0
	s_setprio 1
	v_mfma_f32_16x16x32_bf16 v[116:119], v[170:173], v[186:189], v[116:119]
	v_mfma_f32_16x16x32_bf16 v[112:115], v[178:181], v[186:189], v[112:115]
	v_mfma_f32_16x16x32_bf16 v[100:103], v[170:173], v[194:197], v[100:103]
	v_mfma_f32_16x16x32_bf16 v[96:99], v[178:181], v[194:197], v[96:99]
	v_mfma_f32_16x16x32_bf16 v[84:87], v[170:173], v[202:205], v[84:87]
	v_mfma_f32_16x16x32_bf16 v[80:83], v[178:181], v[202:205], v[80:83]
	v_mfma_f32_16x16x32_bf16 v[68:71], v[170:173], v[214:217], v[68:71]
	v_mfma_f32_16x16x32_bf16 v[64:67], v[178:181], v[214:217], v[64:67]
	v_mfma_f32_16x16x32_bf16 v[116:119], v[174:177], v[190:193], v[116:119]
	v_mfma_f32_16x16x32_bf16 v[112:115], v[182:185], v[190:193], v[112:115]
	v_mfma_f32_16x16x32_bf16 v[100:103], v[174:177], v[198:201], v[100:103]
	v_mfma_f32_16x16x32_bf16 v[96:99], v[182:185], v[198:201], v[96:99]
	v_mfma_f32_16x16x32_bf16 v[84:87], v[174:177], v[206:209], v[84:87]
	v_mfma_f32_16x16x32_bf16 v[80:83], v[182:185], v[206:209], v[80:83]
	v_mfma_f32_16x16x32_bf16 v[68:71], v[174:177], v[218:221], v[68:71]
	v_mfma_f32_16x16x32_bf16 v[64:67], v[182:185], v[218:221], v[64:67]
	s_setprio 0
	s_barrier
	s_add_i32 s56, s48, s35
	v_lshl_add_u64 v[144:145], s[24:25], 0, v[132:133]
	s_mov_b32 m0, s56
	ds_read_b128 v[186:189], v152 offset:16384
	ds_read_b128 v[190:193], v152 offset:17408
	ds_read_b128 v[194:197], v152 offset:18432
	ds_read_b128 v[198:201], v152 offset:19456
	ds_read_b128 v[202:205], v152 offset:20480
	ds_read_b128 v[206:209], v152 offset:21504
	ds_read_b128 v[214:217], v152 offset:22528
	ds_read_b128 v[218:221], v152 offset:23552
	global_load_lds_dwordx4 v[144:145], off
	s_add_i32 m0, s56, 0x2000
	s_add_u32 s56, s24, 0x80000
	v_lshl_add_u64 v[210:211], s[24:25], 0, v[128:129]
	s_addc_u32 s57, s25, 0
	s_add_i32 s58, s49, s35
	global_load_lds_dwordx4 v[210:211], off
	v_lshl_add_u64 v[222:223], s[56:57], 0, v[132:133]
	s_mov_b32 m0, s58
	v_lshl_add_u64 v[224:225], s[26:27], 0, v[130:131]
	global_load_lds_dwordx4 v[222:223], off
	v_lshl_add_u64 v[222:223], s[56:57], 0, v[128:129]
	s_add_i32 m0, s58, 0x2000
	s_nop 0
	global_load_lds_dwordx4 v[222:223], off
	v_lshl_add_u64 v[222:223], s[26:27], 0, v[134:135]
	s_mov_b32 m0, s38
	s_nop 0
	global_load_lds_dwordx4 v[222:223], off
	s_mov_b32 m0, s39
	s_nop 0
	global_load_lds_dwordx4 v[224:225], off
	s_waitcnt vmcnt(8)
	s_waitcnt lgkmcnt(0)
	s_barrier
	s_setprio 1
	s_waitcnt lgkmcnt(0)
	v_mfma_f32_16x16x32_bf16 v[60:63], v[154:157], v[186:189], v[60:63]
	v_mfma_f32_16x16x32_bf16 v[56:59], v[162:165], v[186:189], v[56:59]
	v_mfma_f32_16x16x32_bf16 v[44:47], v[154:157], v[194:197], v[44:47]
	v_mfma_f32_16x16x32_bf16 v[40:43], v[162:165], v[194:197], v[40:43]
	v_mfma_f32_16x16x32_bf16 v[28:31], v[154:157], v[202:205], v[28:31]
	v_mfma_f32_16x16x32_bf16 v[24:27], v[162:165], v[202:205], v[24:27]
	v_mfma_f32_16x16x32_bf16 v[12:15], v[154:157], v[214:217], v[12:15]
	v_mfma_f32_16x16x32_bf16 v[8:11], v[162:165], v[214:217], v[8:11]
	v_mfma_f32_16x16x32_bf16 v[60:63], v[158:161], v[190:193], v[60:63]
	v_mfma_f32_16x16x32_bf16 v[56:59], v[166:169], v[190:193], v[56:59]
	v_mfma_f32_16x16x32_bf16 v[44:47], v[158:161], v[198:201], v[44:47]
	v_mfma_f32_16x16x32_bf16 v[40:43], v[166:169], v[198:201], v[40:43]
	v_mfma_f32_16x16x32_bf16 v[28:31], v[158:161], v[206:209], v[28:31]
	v_mfma_f32_16x16x32_bf16 v[24:27], v[166:169], v[206:209], v[24:27]
	v_mfma_f32_16x16x32_bf16 v[12:15], v[158:161], v[218:221], v[12:15]
	v_mfma_f32_16x16x32_bf16 v[8:11], v[166:169], v[218:221], v[8:11]
	s_setprio 0
	s_setprio 1
	v_mfma_f32_16x16x32_bf16 v[52:55], v[170:173], v[186:189], v[52:55]
	v_mfma_f32_16x16x32_bf16 v[48:51], v[178:181], v[186:189], v[48:51]
	v_mfma_f32_16x16x32_bf16 v[36:39], v[170:173], v[194:197], v[36:39]
	v_mfma_f32_16x16x32_bf16 v[32:35], v[178:181], v[194:197], v[32:35]
	v_mfma_f32_16x16x32_bf16 v[20:23], v[170:173], v[202:205], v[20:23]
	v_mfma_f32_16x16x32_bf16 v[16:19], v[178:181], v[202:205], v[16:19]
	v_mfma_f32_16x16x32_bf16 v[4:7], v[170:173], v[214:217], v[4:7]
	v_mfma_f32_16x16x32_bf16 v[0:3], v[178:181], v[214:217], v[0:3]
	v_mfma_f32_16x16x32_bf16 v[52:55], v[174:177], v[190:193], v[52:55]
	v_mfma_f32_16x16x32_bf16 v[48:51], v[182:185], v[190:193], v[48:51]
	v_mfma_f32_16x16x32_bf16 v[36:39], v[174:177], v[198:201], v[36:39]
	v_mfma_f32_16x16x32_bf16 v[32:35], v[182:185], v[198:201], v[32:35]
	v_mfma_f32_16x16x32_bf16 v[20:23], v[174:177], v[206:209], v[20:23]
	v_mfma_f32_16x16x32_bf16 v[16:19], v[182:185], v[206:209], v[16:19]
	v_mfma_f32_16x16x32_bf16 v[4:7], v[174:177], v[218:221], v[4:7]
	v_mfma_f32_16x16x32_bf16 v[0:3], v[182:185], v[218:221], v[0:3]
	s_setprio 0
	s_barrier
	s_add_i32 s56, 0, 0x18000
	v_add_u32_e32 v153, s56, v149
	s_add_i32 s57, 0, 0x1c000
	ds_read_b128 v[154:157], v153
	ds_read_b128 v[158:161], v153 offset:1024
	ds_read_b128 v[162:165], v153 offset:2048
	ds_read_b128 v[166:169], v153 offset:3072
	v_add_u32_e32 v153, s57, v149
	ds_read_b128 v[170:173], v153
	ds_read_b128 v[174:177], v153 offset:1024
	ds_read_b128 v[178:181], v153 offset:2048
	ds_read_b128 v[182:185], v153 offset:3072
	s_add_u32 s26, s26, 0x80000
	s_addc_u32 s27, s27, 0
	s_mov_b32 m0, s40
	v_lshl_add_u64 v[226:227], s[26:27], 0, v[134:135]
	ds_read_b128 v[186:189], v152 offset:32768
	ds_read_b128 v[190:193], v152 offset:33792
	ds_read_b128 v[194:197], v152 offset:34816
	ds_read_b128 v[198:201], v152 offset:35840
	ds_read_b128 v[202:205], v152 offset:36864
	ds_read_b128 v[206:209], v152 offset:37888
	ds_read_b128 v[214:217], v152 offset:38912
	ds_read_b128 v[218:221], v152 offset:39936
	global_load_lds_dwordx4 v[226:227], off
	v_lshl_add_u64 v[226:227], s[26:27], 0, v[130:131]
	s_mov_b32 m0, s41
	s_nop 0
	global_load_lds_dwordx4 v[226:227], off
	s_waitcnt vmcnt(8)
	s_waitcnt lgkmcnt(0)
	s_barrier
	s_setprio 1
	s_waitcnt lgkmcnt(0)
	v_mfma_f32_16x16x32_bf16 v[124:127], v[154:157], v[186:189], v[124:127]
	v_mfma_f32_16x16x32_bf16 v[120:123], v[162:165], v[186:189], v[120:123]
	v_mfma_f32_16x16x32_bf16 v[108:111], v[154:157], v[194:197], v[108:111]
	v_mfma_f32_16x16x32_bf16 v[104:107], v[162:165], v[194:197], v[104:107]
	v_mfma_f32_16x16x32_bf16 v[92:95], v[154:157], v[202:205], v[92:95]
	v_mfma_f32_16x16x32_bf16 v[88:91], v[162:165], v[202:205], v[88:91]
	v_mfma_f32_16x16x32_bf16 v[76:79], v[154:157], v[214:217], v[76:79]
	v_mfma_f32_16x16x32_bf16 v[72:75], v[162:165], v[214:217], v[72:75]
	v_mfma_f32_16x16x32_bf16 v[124:127], v[158:161], v[190:193], v[124:127]
	v_mfma_f32_16x16x32_bf16 v[120:123], v[166:169], v[190:193], v[120:123]
	v_mfma_f32_16x16x32_bf16 v[108:111], v[158:161], v[198:201], v[108:111]
	v_mfma_f32_16x16x32_bf16 v[104:107], v[166:169], v[198:201], v[104:107]
	v_mfma_f32_16x16x32_bf16 v[92:95], v[158:161], v[206:209], v[92:95]
	v_mfma_f32_16x16x32_bf16 v[88:91], v[166:169], v[206:209], v[88:91]
	v_mfma_f32_16x16x32_bf16 v[76:79], v[158:161], v[218:221], v[76:79]
	v_mfma_f32_16x16x32_bf16 v[72:75], v[166:169], v[218:221], v[72:75]
	s_setprio 0
	s_setprio 1
	v_mfma_f32_16x16x32_bf16 v[116:119], v[170:173], v[186:189], v[116:119]
	v_mfma_f32_16x16x32_bf16 v[112:115], v[178:181], v[186:189], v[112:115]
	v_mfma_f32_16x16x32_bf16 v[100:103], v[170:173], v[194:197], v[100:103]
	v_mfma_f32_16x16x32_bf16 v[96:99], v[178:181], v[194:197], v[96:99]
	v_mfma_f32_16x16x32_bf16 v[84:87], v[170:173], v[202:205], v[84:87]
	v_mfma_f32_16x16x32_bf16 v[80:83], v[178:181], v[202:205], v[80:83]
	v_mfma_f32_16x16x32_bf16 v[68:71], v[170:173], v[214:217], v[68:71]
	v_mfma_f32_16x16x32_bf16 v[64:67], v[178:181], v[214:217], v[64:67]
	v_mfma_f32_16x16x32_bf16 v[116:119], v[174:177], v[190:193], v[116:119]
	v_mfma_f32_16x16x32_bf16 v[112:115], v[182:185], v[190:193], v[112:115]
	v_mfma_f32_16x16x32_bf16 v[100:103], v[174:177], v[198:201], v[100:103]
	v_mfma_f32_16x16x32_bf16 v[96:99], v[182:185], v[198:201], v[96:99]
	v_mfma_f32_16x16x32_bf16 v[84:87], v[174:177], v[206:209], v[84:87]
	v_mfma_f32_16x16x32_bf16 v[80:83], v[182:185], v[206:209], v[80:83]
	v_mfma_f32_16x16x32_bf16 v[68:71], v[174:177], v[218:221], v[68:71]
	v_mfma_f32_16x16x32_bf16 v[64:67], v[182:185], v[218:221], v[64:67]
	s_setprio 0
	s_barrier
	s_add_i32 s26, s56, s35
	v_lshl_add_u64 v[144:145], v[144:145], 0, s[4:5]
	s_mov_b32 m0, s26
	ds_read_b128 v[186:189], v152 offset:49152
	ds_read_b128 v[190:193], v152 offset:50176
	ds_read_b128 v[194:197], v152 offset:51200
	ds_read_b128 v[198:201], v152 offset:52224
	ds_read_b128 v[202:205], v152 offset:53248
	ds_read_b128 v[206:209], v152 offset:54272
	ds_read_b128 v[214:217], v152 offset:55296
	ds_read_b128 v[218:221], v152 offset:56320
	global_load_lds_dwordx4 v[144:145], off
	s_add_i32 m0, s26, 0x2000
	s_add_u32 s24, s24, 0x80080
	v_lshl_add_u64 v[144:145], v[210:211], 0, s[4:5]
	s_addc_u32 s25, s25, 0
	s_add_i32 s26, s57, s35
	global_load_lds_dwordx4 v[144:145], off
	v_lshl_add_u64 v[144:145], s[24:25], 0, v[132:133]
	s_mov_b32 m0, s26
	s_nop 0
	global_load_lds_dwordx4 v[144:145], off
	v_lshl_add_u64 v[144:145], s[24:25], 0, v[128:129]
	s_add_i32 m0, s26, 0x2000
	s_nop 0
	global_load_lds_dwordx4 v[144:145], off
	v_lshl_add_u64 v[144:145], v[222:223], 0, s[4:5]
	s_mov_b32 m0, s45
	s_nop 0
	global_load_lds_dwordx4 v[144:145], off
	v_lshl_add_u64 v[144:145], v[224:225], 0, s[4:5]
	s_mov_b32 m0, s46
	s_nop 0
	global_load_lds_dwordx4 v[144:145], off
	s_waitcnt vmcnt(8)
	s_waitcnt lgkmcnt(0)
	s_barrier
	s_setprio 1
	s_waitcnt lgkmcnt(0)
	v_mfma_f32_16x16x32_bf16 v[60:63], v[154:157], v[186:189], v[60:63]
	v_mfma_f32_16x16x32_bf16 v[56:59], v[162:165], v[186:189], v[56:59]
	v_mfma_f32_16x16x32_bf16 v[44:47], v[154:157], v[194:197], v[44:47]
	v_mfma_f32_16x16x32_bf16 v[40:43], v[162:165], v[194:197], v[40:43]
	v_mfma_f32_16x16x32_bf16 v[28:31], v[154:157], v[202:205], v[28:31]
	v_mfma_f32_16x16x32_bf16 v[24:27], v[162:165], v[202:205], v[24:27]
	v_mfma_f32_16x16x32_bf16 v[12:15], v[154:157], v[214:217], v[12:15]
	v_mfma_f32_16x16x32_bf16 v[8:11], v[162:165], v[214:217], v[8:11]
	v_mfma_f32_16x16x32_bf16 v[60:63], v[158:161], v[190:193], v[60:63]
	v_mfma_f32_16x16x32_bf16 v[56:59], v[166:169], v[190:193], v[56:59]
	v_mfma_f32_16x16x32_bf16 v[44:47], v[158:161], v[198:201], v[44:47]
	v_mfma_f32_16x16x32_bf16 v[40:43], v[166:169], v[198:201], v[40:43]
	v_mfma_f32_16x16x32_bf16 v[28:31], v[158:161], v[206:209], v[28:31]
	v_mfma_f32_16x16x32_bf16 v[24:27], v[166:169], v[206:209], v[24:27]
	v_mfma_f32_16x16x32_bf16 v[12:15], v[158:161], v[218:221], v[12:15]
	v_mfma_f32_16x16x32_bf16 v[8:11], v[166:169], v[218:221], v[8:11]
	s_setprio 0
	s_setprio 1
	v_mfma_f32_16x16x32_bf16 v[52:55], v[170:173], v[186:189], v[52:55]
	v_mfma_f32_16x16x32_bf16 v[48:51], v[178:181], v[186:189], v[48:51]
	v_mfma_f32_16x16x32_bf16 v[36:39], v[170:173], v[194:197], v[36:39]
	v_mfma_f32_16x16x32_bf16 v[32:35], v[178:181], v[194:197], v[32:35]
	v_mfma_f32_16x16x32_bf16 v[20:23], v[170:173], v[202:205], v[20:23]
	v_mfma_f32_16x16x32_bf16 v[16:19], v[178:181], v[202:205], v[16:19]
	v_mfma_f32_16x16x32_bf16 v[4:7], v[170:173], v[214:217], v[4:7]
	v_mfma_f32_16x16x32_bf16 v[0:3], v[178:181], v[214:217], v[0:3]
	v_mfma_f32_16x16x32_bf16 v[52:55], v[174:177], v[190:193], v[52:55]
	v_mfma_f32_16x16x32_bf16 v[48:51], v[182:185], v[190:193], v[48:51]
	v_mfma_f32_16x16x32_bf16 v[36:39], v[174:177], v[198:201], v[36:39]
	v_mfma_f32_16x16x32_bf16 v[32:35], v[182:185], v[198:201], v[32:35]
	v_mfma_f32_16x16x32_bf16 v[20:23], v[174:177], v[206:209], v[20:23]
	v_mfma_f32_16x16x32_bf16 v[16:19], v[182:185], v[206:209], v[16:19]
	v_mfma_f32_16x16x32_bf16 v[4:7], v[174:177], v[218:221], v[4:7]
	v_mfma_f32_16x16x32_bf16 v[0:3], v[182:185], v[218:221], v[0:3]
	s_setprio 0
	s_barrier
	s_add_i32 s55, s55, 2
	s_add_u32 s22, s22, 0x100
	s_addc_u32 s23, s23, 0
	s_add_u32 s53, s53, 0x100
	s_addc_u32 s54, s54, 0
	s_cmp_gt_u32 s55, s99
	s_cbranch_scc0 .LBB0_826
	s_and_b64 vcc, exec, s[10:11]
	s_cbranch_vccz .LBB0_829
	s_barrier
.LBB0_829:
	s_cmp_lt_i32 s100, 0
	s_cbranch_scc1 .Lsk7_epi
	s_and_b32 s54, s100, 0x7f
	s_lshr_b32 s61, s100, 7
	s_lshl_b32 s55, s54, 18
	s_add_u32 s56, s76, 0x29189000
	s_addc_u32 s57, s77, 0
	s_add_u32 s56, s56, s55
	s_addc_u32 s57, s57, 0
	s_lshl_b32 s55, s54, 6
	s_add_u32 s58, s76, 0x8000
	s_addc_u32 s59, s77, 0
	s_add_u32 s58, s58, s55
	s_addc_u32 s59, s59, 0
	s_lshl_b32 s55, s93, 10
	v_lshl_add_u32 v224, v146, 4, s55
	s_cmp_lg_u32 s61, 0
	s_cbranch_scc1 .Lsk7_cons
	global_store_dwordx4 v224, v[0:3], s[56:57] sc1
	s_add_u32 s56, s56, 0x2000
	s_addc_u32 s57, s57, 0
	global_store_dwordx4 v224, v[4:7], s[56:57] sc1
	s_add_u32 s56, s56, 0x2000
	s_addc_u32 s57, s57, 0
	global_store_dwordx4 v224, v[8:11], s[56:57] sc1
	s_add_u32 s56, s56, 0x2000
	s_addc_u32 s57, s57, 0
	global_store_dwordx4 v224, v[12:15], s[56:57] sc1
	s_add_u32 s56, s56, 0x2000
	s_addc_u32 s57, s57, 0
	global_store_dwordx4 v224, v[16:19], s[56:57] sc1
	s_add_u32 s56, s56, 0x2000
	s_addc_u32 s57, s57, 0
	global_store_dwordx4 v224, v[20:23], s[56:57] sc1
	s_add_u32 s56, s56, 0x2000
	s_addc_u32 s57, s57, 0
	global_store_dwordx4 v224, v[24:27], s[56:57] sc1
	s_add_u32 s56, s56, 0x2000
	s_addc_u32 s57, s57, 0
	global_store_dwordx4 v224, v[28:31], s[56:57] sc1
	s_add_u32 s56, s56, 0x2000
	s_addc_u32 s57, s57, 0
	global_store_dwordx4 v224, v[32:35], s[56:57] sc1
	s_add_u32 s56, s56, 0x2000
	s_addc_u32 s57, s57, 0
	global_store_dwordx4 v224, v[36:39], s[56:57] sc1
	s_add_u32 s56, s56, 0x2000
	s_addc_u32 s57, s57, 0
	global_store_dwordx4 v224, v[40:43], s[56:57] sc1
	s_add_u32 s56, s56, 0x2000
	s_addc_u32 s57, s57, 0
	global_store_dwordx4 v224, v[44:47], s[56:57] sc1
	s_add_u32 s56, s56, 0x2000
	s_addc_u32 s57, s57, 0
	global_store_dwordx4 v224, v[48:51], s[56:57] sc1
	s_add_u32 s56, s56, 0x2000
	s_addc_u32 s57, s57, 0
	global_store_dwordx4 v224, v[52:55], s[56:57] sc1
	s_add_u32 s56, s56, 0x2000
	s_addc_u32 s57, s57, 0
	global_store_dwordx4 v224, v[56:59], s[56:57] sc1
	s_add_u32 s56, s56, 0x2000
	s_addc_u32 s57, s57, 0
	global_store_dwordx4 v224, v[60:63], s[56:57] sc1
	s_add_u32 s56, s56, 0x2000
	s_addc_u32 s57, s57, 0
	global_store_dwordx4 v224, v[64:67], s[56:57] sc1
	s_add_u32 s56, s56, 0x2000
	s_addc_u32 s57, s57, 0
	global_store_dwordx4 v224, v[68:71], s[56:57] sc1
	s_add_u32 s56, s56, 0x2000
	s_addc_u32 s57, s57, 0
	global_store_dwordx4 v224, v[72:75], s[56:57] sc1
	s_add_u32 s56, s56, 0x2000
	s_addc_u32 s57, s57, 0
	global_store_dwordx4 v224, v[76:79], s[56:57] sc1
	s_add_u32 s56, s56, 0x2000
	s_addc_u32 s57, s57, 0
	global_store_dwordx4 v224, v[80:83], s[56:57] sc1
	s_add_u32 s56, s56, 0x2000
	s_addc_u32 s57, s57, 0
	global_store_dwordx4 v224, v[84:87], s[56:57] sc1
	s_add_u32 s56, s56, 0x2000
	s_addc_u32 s57, s57, 0
	global_store_dwordx4 v224, v[88:91], s[56:57] sc1
	s_add_u32 s56, s56, 0x2000
	s_addc_u32 s57, s57, 0
	global_store_dwordx4 v224, v[92:95], s[56:57] sc1
	s_add_u32 s56, s56, 0x2000
	s_addc_u32 s57, s57, 0
	global_store_dwordx4 v224, v[96:99], s[56:57] sc1
	s_add_u32 s56, s56, 0x2000
	s_addc_u32 s57, s57, 0
	global_store_dwordx4 v224, v[100:103], s[56:57] sc1
	s_add_u32 s56, s56, 0x2000
	s_addc_u32 s57, s57, 0
	global_store_dwordx4 v224, v[104:107], s[56:57] sc1
	s_add_u32 s56, s56, 0x2000
	s_addc_u32 s57, s57, 0
	global_store_dwordx4 v224, v[108:111], s[56:57] sc1
	s_add_u32 s56, s56, 0x2000
	s_addc_u32 s57, s57, 0
	global_store_dwordx4 v224, v[112:115], s[56:57] sc1
	s_add_u32 s56, s56, 0x2000
	s_addc_u32 s57, s57, 0
	global_store_dwordx4 v224, v[116:119], s[56:57] sc1
	s_add_u32 s56, s56, 0x2000
	s_addc_u32 s57, s57, 0
	global_store_dwordx4 v224, v[120:123], s[56:57] sc1
	s_add_u32 s56, s56, 0x2000
	s_addc_u32 s57, s57, 0
	global_store_dwordx4 v224, v[124:127], s[56:57] sc1
	s_add_u32 s56, s56, 0x2000
	s_addc_u32 s57, s57, 0
	s_waitcnt vmcnt(0)
	s_barrier
	s_cmp_lg_u32 s93, 0
	s_cbranch_scc1 .Lsk7_pdone
	s_mov_b64 s[54:55], exec
	s_mov_b64 exec, 1
	v_mov_b32_e32 v225, 0
	v_mov_b32_e32 v226, 1
	global_atomic_add v225, v226, s[58:59]
	s_mov_b64 exec, s[54:55]
.Lsk7_pdone:
	s_branch .LBB0_832
.Lsk7_cons:
	s_cmp_lg_u32 s93, 0
	s_cbranch_scc1 .Lsk7_cw
	s_waitcnt vmcnt(0)
	buffer_inv sc1
	v_mov_b32_e32 v225, 0
	s_mov_b32 s54, 0
.Lsk7_poll:
	global_load_dword v226, v225, s[58:59] sc1
	s_waitcnt vmcnt(0)
	v_readfirstlane_b32 s55, v226
	s_cmp_lg_u32 s55, 0
	s_cbranch_scc1 .Lsk7_cw
	s_sleep 1
	s_add_u32 s54, s54, 1
	s_cmp_lt_u32 s54, 0x80000
	s_cbranch_scc1 .Lsk7_poll
.Lsk7_cw:
	s_waitcnt vmcnt(0)
	s_barrier
	global_load_dwordx4 v[156:159], v224, s[56:57]
	s_add_u32 s56, s56, 0x2000
	s_addc_u32 s57, s57, 0
	global_load_dwordx4 v[160:163], v224, s[56:57]
	s_add_u32 s56, s56, 0x2000
	s_addc_u32 s57, s57, 0
	global_load_dwordx4 v[164:167], v224, s[56:57]
	s_add_u32 s56, s56, 0x2000
	s_addc_u32 s57, s57, 0
	global_load_dwordx4 v[168:171], v224, s[56:57]
	s_add_u32 s56, s56, 0x2000
	s_addc_u32 s57, s57, 0
	global_load_dwordx4 v[172:175], v224, s[56:57]
	s_add_u32 s56, s56, 0x2000
	s_addc_u32 s57, s57, 0
	global_load_dwordx4 v[176:179], v224, s[56:57]
	s_add_u32 s56, s56, 0x2000
	s_addc_u32 s57, s57, 0
	global_load_dwordx4 v[180:183], v224, s[56:57]
	s_add_u32 s56, s56, 0x2000
	s_addc_u32 s57, s57, 0
	global_load_dwordx4 v[184:187], v224, s[56:57]
	s_add_u32 s56, s56, 0x2000
	s_addc_u32 s57, s57, 0
	global_load_dwordx4 v[188:191], v224, s[56:57]
	s_add_u32 s56, s56, 0x2000
	s_addc_u32 s57, s57, 0
	global_load_dwordx4 v[192:195], v224, s[56:57]
	s_add_u32 s56, s56, 0x2000
	s_addc_u32 s57, s57, 0
	global_load_dwordx4 v[196:199], v224, s[56:57]
	s_add_u32 s56, s56, 0x2000
	s_addc_u32 s57, s57, 0
	global_load_dwordx4 v[200:203], v224, s[56:57]
	s_add_u32 s56, s56, 0x2000
	s_addc_u32 s57, s57, 0
	global_load_dwordx4 v[204:207], v224, s[56:57]
	s_add_u32 s56, s56, 0x2000
	s_addc_u32 s57, s57, 0
	global_load_dwordx4 v[208:211], v224, s[56:57]
	s_add_u32 s56, s56, 0x2000
	s_addc_u32 s57, s57, 0
	global_load_dwordx4 v[216:219], v224, s[56:57]
	s_add_u32 s56, s56, 0x2000
	s_addc_u32 s57, s57, 0
	global_load_dwordx4 v[220:223], v224, s[56:57]
	s_add_u32 s56, s56, 0x2000
	s_addc_u32 s57, s57, 0
	s_waitcnt vmcnt(15)
	v_add_f32_e32 v0, v0, v156
	v_add_f32_e32 v1, v1, v157
	v_add_f32_e32 v2, v2, v158
	v_add_f32_e32 v3, v3, v159
	s_waitcnt vmcnt(14)
	v_add_f32_e32 v4, v4, v160
	v_add_f32_e32 v5, v5, v161
	v_add_f32_e32 v6, v6, v162
	v_add_f32_e32 v7, v7, v163
	s_waitcnt vmcnt(13)
	v_add_f32_e32 v8, v8, v164
	v_add_f32_e32 v9, v9, v165
	v_add_f32_e32 v10, v10, v166
	v_add_f32_e32 v11, v11, v167
	s_waitcnt vmcnt(12)
	v_add_f32_e32 v12, v12, v168
	v_add_f32_e32 v13, v13, v169
	v_add_f32_e32 v14, v14, v170
	v_add_f32_e32 v15, v15, v171
	s_waitcnt vmcnt(11)
	v_add_f32_e32 v16, v16, v172
	v_add_f32_e32 v17, v17, v173
	v_add_f32_e32 v18, v18, v174
	v_add_f32_e32 v19, v19, v175
	s_waitcnt vmcnt(10)
	v_add_f32_e32 v20, v20, v176
	v_add_f32_e32 v21, v21, v177
	v_add_f32_e32 v22, v22, v178
	v_add_f32_e32 v23, v23, v179
	s_waitcnt vmcnt(9)
	v_add_f32_e32 v24, v24, v180
	v_add_f32_e32 v25, v25, v181
	v_add_f32_e32 v26, v26, v182
	v_add_f32_e32 v27, v27, v183
	s_waitcnt vmcnt(8)
	v_add_f32_e32 v28, v28, v184
	v_add_f32_e32 v29, v29, v185
	v_add_f32_e32 v30, v30, v186
	v_add_f32_e32 v31, v31, v187
	s_waitcnt vmcnt(7)
	v_add_f32_e32 v32, v32, v188
	v_add_f32_e32 v33, v33, v189
	v_add_f32_e32 v34, v34, v190
	v_add_f32_e32 v35, v35, v191
	s_waitcnt vmcnt(6)
	v_add_f32_e32 v36, v36, v192
	v_add_f32_e32 v37, v37, v193
	v_add_f32_e32 v38, v38, v194
	v_add_f32_e32 v39, v39, v195
	s_waitcnt vmcnt(5)
	v_add_f32_e32 v40, v40, v196
	v_add_f32_e32 v41, v41, v197
	v_add_f32_e32 v42, v42, v198
	v_add_f32_e32 v43, v43, v199
	s_waitcnt vmcnt(4)
	v_add_f32_e32 v44, v44, v200
	v_add_f32_e32 v45, v45, v201
	v_add_f32_e32 v46, v46, v202
	v_add_f32_e32 v47, v47, v203
	s_waitcnt vmcnt(3)
	v_add_f32_e32 v48, v48, v204
	v_add_f32_e32 v49, v49, v205
	v_add_f32_e32 v50, v50, v206
	v_add_f32_e32 v51, v51, v207
	s_waitcnt vmcnt(2)
	v_add_f32_e32 v52, v52, v208
	v_add_f32_e32 v53, v53, v209
	v_add_f32_e32 v54, v54, v210
	v_add_f32_e32 v55, v55, v211
	s_waitcnt vmcnt(1)
	v_add_f32_e32 v56, v56, v216
	v_add_f32_e32 v57, v57, v217
	v_add_f32_e32 v58, v58, v218
	v_add_f32_e32 v59, v59, v219
	s_waitcnt vmcnt(0)
	v_add_f32_e32 v60, v60, v220
	v_add_f32_e32 v61, v61, v221
	v_add_f32_e32 v62, v62, v222
	v_add_f32_e32 v63, v63, v223
	global_load_dwordx4 v[156:159], v224, s[56:57]
	s_add_u32 s56, s56, 0x2000
	s_addc_u32 s57, s57, 0
	global_load_dwordx4 v[160:163], v224, s[56:57]
	s_add_u32 s56, s56, 0x2000
	s_addc_u32 s57, s57, 0
	global_load_dwordx4 v[164:167], v224, s[56:57]
	s_add_u32 s56, s56, 0x2000
	s_addc_u32 s57, s57, 0
	global_load_dwordx4 v[168:171], v224, s[56:57]
	s_add_u32 s56, s56, 0x2000
	s_addc_u32 s57, s57, 0
	global_load_dwordx4 v[172:175], v224, s[56:57]
	s_add_u32 s56, s56, 0x2000
	s_addc_u32 s57, s57, 0
	global_load_dwordx4 v[176:179], v224, s[56:57]
	s_add_u32 s56, s56, 0x2000
	s_addc_u32 s57, s57, 0
	global_load_dwordx4 v[180:183], v224, s[56:57]
	s_add_u32 s56, s56, 0x2000
	s_addc_u32 s57, s57, 0
	global_load_dwordx4 v[184:187], v224, s[56:57]
	s_add_u32 s56, s56, 0x2000
	s_addc_u32 s57, s57, 0
	global_load_dwordx4 v[188:191], v224, s[56:57]
	s_add_u32 s56, s56, 0x2000
	s_addc_u32 s57, s57, 0
	global_load_dwordx4 v[192:195], v224, s[56:57]
	s_add_u32 s56, s56, 0x2000
	s_addc_u32 s57, s57, 0
	global_load_dwordx4 v[196:199], v224, s[56:57]
	s_add_u32 s56, s56, 0x2000
	s_addc_u32 s57, s57, 0
	global_load_dwordx4 v[200:203], v224, s[56:57]
	s_add_u32 s56, s56, 0x2000
	s_addc_u32 s57, s57, 0
	global_load_dwordx4 v[204:207], v224, s[56:57]
	s_add_u32 s56, s56, 0x2000
	s_addc_u32 s57, s57, 0
	global_load_dwordx4 v[208:211], v224, s[56:57]
	s_add_u32 s56, s56, 0x2000
	s_addc_u32 s57, s57, 0
	global_load_dwordx4 v[216:219], v224, s[56:57]
	s_add_u32 s56, s56, 0x2000
	s_addc_u32 s57, s57, 0
	global_load_dwordx4 v[220:223], v224, s[56:57]
	s_add_u32 s56, s56, 0x2000
	s_addc_u32 s57, s57, 0
	s_waitcnt vmcnt(15)
	v_add_f32_e32 v64, v64, v156
	v_add_f32_e32 v65, v65, v157
	v_add_f32_e32 v66, v66, v158
	v_add_f32_e32 v67, v67, v159
	s_waitcnt vmcnt(14)
	v_add_f32_e32 v68, v68, v160
	v_add_f32_e32 v69, v69, v161
	v_add_f32_e32 v70, v70, v162
	v_add_f32_e32 v71, v71, v163
	s_waitcnt vmcnt(13)
	v_add_f32_e32 v72, v72, v164
	v_add_f32_e32 v73, v73, v165
	v_add_f32_e32 v74, v74, v166
	v_add_f32_e32 v75, v75, v167
	s_waitcnt vmcnt(12)
	v_add_f32_e32 v76, v76, v168
	v_add_f32_e32 v77, v77, v169
	v_add_f32_e32 v78, v78, v170
	v_add_f32_e32 v79, v79, v171
	s_waitcnt vmcnt(11)
	v_add_f32_e32 v80, v80, v172
	v_add_f32_e32 v81, v81, v173
	v_add_f32_e32 v82, v82, v174
	v_add_f32_e32 v83, v83, v175
	s_waitcnt vmcnt(10)
	v_add_f32_e32 v84, v84, v176
	v_add_f32_e32 v85, v85, v177
	v_add_f32_e32 v86, v86, v178
	v_add_f32_e32 v87, v87, v179
	s_waitcnt vmcnt(9)
	v_add_f32_e32 v88, v88, v180
	v_add_f32_e32 v89, v89, v181
	v_add_f32_e32 v90, v90, v182
	v_add_f32_e32 v91, v91, v183
	s_waitcnt vmcnt(8)
	v_add_f32_e32 v92, v92, v184
	v_add_f32_e32 v93, v93, v185
	v_add_f32_e32 v94, v94, v186
	v_add_f32_e32 v95, v95, v187
	s_waitcnt vmcnt(7)
	v_add_f32_e32 v96, v96, v188
	v_add_f32_e32 v97, v97, v189
	v_add_f32_e32 v98, v98, v190
	v_add_f32_e32 v99, v99, v191
	s_waitcnt vmcnt(6)
	v_add_f32_e32 v100, v100, v192
	v_add_f32_e32 v101, v101, v193
	v_add_f32_e32 v102, v102, v194
	v_add_f32_e32 v103, v103, v195
	s_waitcnt vmcnt(5)
	v_add_f32_e32 v104, v104, v196
	v_add_f32_e32 v105, v105, v197
	v_add_f32_e32 v106, v106, v198
	v_add_f32_e32 v107, v107, v199
	s_waitcnt vmcnt(4)
	v_add_f32_e32 v108, v108, v200
	v_add_f32_e32 v109, v109, v201
	v_add_f32_e32 v110, v110, v202
	v_add_f32_e32 v111, v111, v203
	s_waitcnt vmcnt(3)
	v_add_f32_e32 v112, v112, v204
	v_add_f32_e32 v113, v113, v205
	v_add_f32_e32 v114, v114, v206
	v_add_f32_e32 v115, v115, v207
	s_waitcnt vmcnt(2)
	v_add_f32_e32 v116, v116, v208
	v_add_f32_e32 v117, v117, v209
	v_add_f32_e32 v118, v118, v210
	v_add_f32_e32 v119, v119, v211
	s_waitcnt vmcnt(1)
	v_add_f32_e32 v120, v120, v216
	v_add_f32_e32 v121, v121, v217
	v_add_f32_e32 v122, v122, v218
	v_add_f32_e32 v123, v123, v219
	s_waitcnt vmcnt(0)
	v_add_f32_e32 v124, v124, v220
	v_add_f32_e32 v125, v125, v221
	v_add_f32_e32 v126, v126, v222
	v_add_f32_e32 v127, v127, v223

	.amdhsa_kernel _Z10fwd_kernel6Params
		.amdhsa_group_segment_fixed_size 0
		.amdhsa_private_segment_fixed_size 0
		.amdhsa_kernarg_size 464
		.amdhsa_user_sgpr_count 2
		.amdhsa_user_sgpr_dispatch_ptr 0
		.amdhsa_user_sgpr_queue_ptr 0
		.amdhsa_user_sgpr_kernarg_segment_ptr 1
		.amdhsa_user_sgpr_dispatch_id 0
		.amdhsa_user_sgpr_kernarg_preload_length 0
		.amdhsa_user_sgpr_kernarg_preload_offset 0
		.amdhsa_user_sgpr_private_segment_size 0
		.amdhsa_uses_dynamic_stack 0
		.amdhsa_enable_private_segment 0
		.amdhsa_system_sgpr_workgroup_id_x 1
		.amdhsa_system_sgpr_workgroup_id_y 0
		.amdhsa_system_sgpr_workgroup_id_z 0
		.amdhsa_system_sgpr_workgroup_info 0
		.amdhsa_system_vgpr_workitem_id 2
		.amdhsa_next_free_vgpr 245
		.amdhsa_next_free_sgpr 102
		.amdhsa_accum_offset 248
		.amdhsa_reserve_vcc 1
		.amdhsa_float_round_mode_32 0
		.amdhsa_float_round_mode_16_64 0
		.amdhsa_float_denorm_mode_32 3
		.amdhsa_float_denorm_mode_16_64 3
		.amdhsa_dx10_clamp 1
		.amdhsa_ieee_mode 1
		.amdhsa_fp16_overflow 0
		.amdhsa_tg_split 0
		.amdhsa_exception_fp_ieee_invalid_op 0
		.amdhsa_exception_fp_denorm_src 0
		.amdhsa_exception_fp_ieee_div_zero 0
		.amdhsa_exception_fp_ieee_overflow 0
		.amdhsa_exception_fp_ieee_underflow 0
		.amdhsa_exception_fp_ieee_inexact 0
		.amdhsa_exception_int_div_zero 0
	.end_amdhsa_kernel

amdhsa.kernels:
  - .agpr_count:     0
    .args:
      - .offset:         0
        .size:           208
        .value_kind:     by_value
      - .offset:         208
        .size:           4
        .value_kind:     hidden_block_count_x
      - .offset:         212
        .size:           4
        .value_kind:     hidden_block_count_y
      - .offset:         216
        .size:           4
        .value_kind:     hidden_block_count_z
      - .offset:         220
        .size:           2
        .value_kind:     hidden_group_size_x
      - .offset:         222
        .size:           2
        .value_kind:     hidden_group_size_y
      - .offset:         224
        .size:           2
        .value_kind:     hidden_group_size_z
      - .offset:         226
        .size:           2
        .value_kind:     hidden_remainder_x
      - .offset:         228
        .size:           2
        .value_kind:     hidden_remainder_y
      - .offset:         230
        .size:           2
        .value_kind:     hidden_remainder_z
      - .offset:         248
        .size:           8
        .value_kind:     hidden_global_offset_x
      - .offset:         256
        .size:           8
        .value_kind:     hidden_global_offset_y
      - .offset:         264
        .size:           8
        .value_kind:     hidden_global_offset_z
      - .offset:         272
        .size:           2
        .value_kind:     hidden_grid_dims
      - .offset:         296
        .size:           8
        .value_kind:     hidden_multigrid_sync_arg
      - .offset:         328
        .size:           4
        .value_kind:     hidden_dynamic_lds_size
    .group_segment_fixed_size: 0
    .kernarg_segment_align: 8
    .kernarg_segment_size: 464
    .language:       OpenCL C
    .language_version:
      - 2
      - 0
    .max_flat_workgroup_size: 512
    .name:           _Z10fwd_kernel6Params
    .private_segment_fixed_size: 0
    .sgpr_count:     108
    .sgpr_spill_count: 137
    .symbol:         _Z10fwd_kernel6Params.kd
    .uniform_work_group_size: 1
    .uses_dynamic_stack: false
    .vgpr_count:     245
    .vgpr_spill_count: 0
    .wavefront_size: 64
